# attention: peeled first-tile P.V and trailing-wave final P.V also batch their V fragment reads (counted lgkmcnt)
# speedup vs baseline: 1.0019x; 1.0019x over previous
; __device__ __forceinline__ void pv(f32x16 (&o)[2], AT_LAS const char* vp, const u32x4& pw0, const u32x4& pw1, const u32x4& pw2, const u32x4& pw3) {
; #pragma unroll
;     for (int d0 = 0; d0 < 2; ++d0) { s16x4 lo[4], hh[4];
; #pragma unroll
; template <int THRL>
; __device__ __forceinline__ void attn_item(int b, int h, int s, const bf16_t* Q, const bf16_t* KN, const bf16_t* KR, const bf16_t* V, const float* goa  , bf16_t* Y, float* ssqy, AT_LAS char* shm, int wid0) {
;     ...
;                 float ma = max3f(p0[0], p0[1], p1[0]), mb = max3f(p0[2], p0[3], p1[1]); ma = max3f(ma, p1[2], p1[3]);
; #pragma unroll
;                 for (int r = 4; r < 16; r += 4) { ma = max3f(ma, p0[r], p0[r + 1]); mb = max3f(mb, p0[r + 2], p0[r + 3]); ma = max3f(ma, p1[r], p1[r + 1]); mb = max3f(mb, p1[r + 2], p1[r + 3]); }
;                 float rm = fmaxf(ma, mb);
;                 { auto rr = __builtin_amdgcn_permlane32_swap(__float_as_uint(rm), __float_as_uint(rm), false, false); rm = fmaxf(__uint_as_float(rr[0]), __uint_as_float(rr[1])); }
;                 if (t == 0 || __any(rm > (float)THRL)) {
;                     const float dl = (t == 0) ? rm : fmaxf(rm, 0.f); mhat += dl;
; #pragma unroll
;                     for (int r = 0; r < 16; ++r) { p0[r] -= dl; p1[r] -= dl; negm[r] = -mhat; }
;                     asm volatile("" : "+v"(negm));
;                     if (t > 0) { const float f = __builtin_amdgcn_exp2f(-dl); l_reg *= f; if (hi == 0) wsf[r32] = f; asm volatile("s_waitcnt lgkmcnt(0)" ::: "memory");
; #pragma unroll
;                         for (int r = 0; r < 16; ++r) { const float fr_ = wsf[crow(r, hi)]; o[0][r] *= fr_; o[1][r] *= fr_; } }
;                 }
;                 float sacc = 0.f;
; #pragma unroll
;                 for (int r = 0; r < 16; ++r) { p0[r] = __builtin_amdgcn_exp2f(p0[r]); p1[r] = __builtin_amdgcn_exp2f(p1[r]); sacc += p0[r] + p1[r]; }
;                 l_reg += sacc;
;     ...
;                 pw0 = (u32x4){AT_PK(p0, 0), AT_PK(p0, 2), AT_PK(p0, 4), AT_PK(p0, 6)}; pw1 = (u32x4){AT_PK(p0, 8), AT_PK(p0, 10), AT_PK(p0, 12), AT_PK(p0, 14)};
;                 pw2 = (u32x4){AT_PK(p1, 0), AT_PK(p1, 2), AT_PK(p1, 4), AT_PK(p1, 6)}; pw3 = (u32x4){AT_PK(p1, 8), AT_PK(p1, 10), AT_PK(p1, 12), AT_PK(p1, 14)};
;     ...
;                 if (late) have = true;
;                 else pv(o, vp0 + (t & 3) * VSLOTB, pw0, pw1, pw2, pw3);
.LBB13_756:
	v_max3_f32 v0, v18, v19, v34
	v_max3_f32 v2, v20, v21, v35
	s_and_b64 vcc, exec, s[76:77]
	v_max3_f32 v0, v0, v36, v37
	v_max3_f32 v2, v2, v24, v25
	s_nop 0
	v_max3_f32 v0, v0, v22, v23
	v_max3_f32 v2, v2, v40, v41
	s_nop 0
	v_max3_f32 v0, v0, v38, v39
	v_max3_f32 v2, v2, v28, v29
	s_nop 0
	v_max3_f32 v0, v0, v26, v27
	v_max3_f32 v2, v2, v44, v45
	s_nop 0
	v_max3_f32 v0, v0, v42, v43
	v_max3_f32 v2, v2, v32, v33
	s_nop 0
	v_max3_f32 v0, v0, v30, v31
	v_max3_f32 v2, v2, v48, v49
	s_nop 0
	v_max3_f32 v0, v0, v46, v47
	v_max_f32_e32 v2, v2, v2
	v_max_f32_e32 v0, v0, v0
	v_max_f32_e32 v0, v0, v2
	v_mov_b32_e32 v2, v0
	s_nop 1
	v_permlane32_swap_b32_e32 v0, v2
	v_max_f32_e32 v2, v2, v2
	v_max_f32_e32 v0, v0, v0
	v_max_f32_e32 v2, v0, v2
	v_sub_f32_e32 v0, v34, v2
	v_sub_f32_e32 v4, v18, v2
	v_sub_f32_e32 v3, v35, v2
	v_sub_f32_e32 v5, v19, v2
	v_exp_f32_e32 v18, v4
	v_exp_f32_e32 v34, v0
	v_exp_f32_e32 v156, v5
	v_exp_f32_e32 v0, v3
	v_sub_f32_e32 v6, v36, v2
	v_add_f32_e32 v157, v18, v34
	v_sub_f32_e32 v3, v20, v2
	v_pk_add_f32 v[4:5], v[156:157], v[0:1]
	v_sub_f32_e32 v7, v37, v2
	v_sub_f32_e32 v19, v21, v2
	v_pk_add_f32 v[154:155], v[4:5], v[4:5] op_sel_hi:[0,1]
	v_exp_f32_e32 v20, v3
	v_exp_f32_e32 v36, v6
	v_exp_f32_e32 v160, v19
	v_exp_f32_e32 v154, v7
	v_sub_f32_e32 v8, v38, v2
	v_add_f32_e32 v161, v20, v36
	v_sub_f32_e32 v3, v22, v2
	v_pk_add_f32 v[4:5], v[160:161], v[154:155]
	v_sub_f32_e32 v9, v39, v2
	v_sub_f32_e32 v6, v23, v2
	v_pk_add_f32 v[158:159], v[4:5], v[4:5] op_sel_hi:[0,1]
	v_exp_f32_e32 v22, v3
	v_exp_f32_e32 v38, v8
	v_exp_f32_e32 v164, v6
	v_exp_f32_e32 v158, v9
	v_sub_f32_e32 v10, v40, v2
	v_add_f32_e32 v165, v22, v38
	v_sub_f32_e32 v3, v24, v2
	v_pk_add_f32 v[4:5], v[164:165], v[158:159]
	v_sub_f32_e32 v11, v41, v2
	v_sub_f32_e32 v6, v25, v2
	v_pk_add_f32 v[162:163], v[4:5], v[4:5] op_sel_hi:[0,1]
	v_exp_f32_e32 v24, v3
	v_exp_f32_e32 v40, v10
	v_exp_f32_e32 v168, v6
	v_exp_f32_e32 v162, v11
	v_sub_f32_e32 v12, v42, v2
	v_add_f32_e32 v169, v24, v40
	v_sub_f32_e32 v3, v26, v2
	v_pk_add_f32 v[4:5], v[168:169], v[162:163]
	v_sub_f32_e32 v13, v43, v2
	v_sub_f32_e32 v6, v27, v2
	v_pk_add_f32 v[166:167], v[4:5], v[4:5] op_sel_hi:[0,1]
	v_exp_f32_e32 v26, v3
	v_exp_f32_e32 v42, v12
	v_exp_f32_e32 v172, v6
	v_exp_f32_e32 v166, v13
	v_sub_f32_e32 v14, v44, v2
	v_add_f32_e32 v173, v26, v42
	v_sub_f32_e32 v3, v28, v2
	v_pk_add_f32 v[4:5], v[172:173], v[166:167]
	v_sub_f32_e32 v15, v45, v2
	v_sub_f32_e32 v6, v29, v2
	v_pk_add_f32 v[170:171], v[4:5], v[4:5] op_sel_hi:[0,1]
	v_exp_f32_e32 v28, v3
	v_exp_f32_e32 v44, v14
	v_exp_f32_e32 v176, v6
	v_exp_f32_e32 v170, v15
	v_sub_f32_e32 v16, v46, v2
	v_add_f32_e32 v177, v28, v44
	v_sub_f32_e32 v3, v30, v2
	v_pk_add_f32 v[4:5], v[176:177], v[170:171]
	v_sub_f32_e32 v17, v47, v2
	v_sub_f32_e32 v6, v31, v2
	v_pk_add_f32 v[174:175], v[4:5], v[4:5] op_sel_hi:[0,1]
	v_exp_f32_e32 v30, v3
	v_exp_f32_e32 v46, v16
	v_exp_f32_e32 v180, v6
	v_exp_f32_e32 v174, v17
	v_sub_f32_e32 v35, v48, v2
	v_add_f32_e32 v181, v30, v46
	v_sub_f32_e32 v3, v32, v2
	v_pk_add_f32 v[4:5], v[180:181], v[174:175]
	v_sub_f32_e32 v37, v49, v2
	v_sub_f32_e32 v6, v33, v2
	v_pk_add_f32 v[178:179], v[4:5], v[4:5] op_sel_hi:[0,1]
	v_exp_f32_e32 v32, v3
	v_exp_f32_e32 v48, v35
	v_exp_f32_e32 v182, v6
	v_exp_f32_e32 v178, v37
	v_cvt_pk_bf16_f32 v110, v18, v156
	v_add_f32_e32 v183, v32, v48
	v_cvt_pk_bf16_f32 v111, v20, v160
	v_pk_add_f32 v[4:5], v[182:183], v[178:179]
	v_cvt_pk_bf16_f32 v112, v22, v164
	v_pk_add_f32 v[4:5], v[4:5], v[4:5] op_sel_hi:[0,1]
	v_mov_b32_e32 v3, v5
	v_pk_add_f32 v[152:153], v[2:3], 0 op_sel_hi:[1,0]
	v_cvt_pk_bf16_f32 v113, v24, v168
	v_xor_b32_e32 v66, 0x80000000, v152
	v_mov_b32_e32 v67, v66
	v_mov_b32_e32 v68, v66
	v_mov_b32_e32 v69, v66
	v_mov_b32_e32 v70, v66
	v_mov_b32_e32 v71, v66
	v_mov_b32_e32 v72, v66
	v_mov_b32_e32 v73, v66
	v_mov_b32_e32 v74, v66
	v_mov_b32_e32 v75, v66
	v_mov_b32_e32 v76, v66
	v_mov_b32_e32 v77, v66
	v_mov_b32_e32 v78, v66
	v_mov_b32_e32 v79, v66
	v_mov_b32_e32 v80, v66
	v_mov_b32_e32 v81, v66
	v_cvt_pk_bf16_f32 v106, v26, v172
	v_cvt_pk_bf16_f32 v107, v28, v176
	v_cvt_pk_bf16_f32 v108, v30, v180
	v_cvt_pk_bf16_f32 v109, v32, v182
	v_cvt_pk_bf16_f32 v118, v34, v0
	v_cvt_pk_bf16_f32 v119, v36, v154
	v_cvt_pk_bf16_f32 v120, v38, v158
	v_cvt_pk_bf16_f32 v121, v40, v162
	v_cvt_pk_bf16_f32 v114, v42, v166
	v_cvt_pk_bf16_f32 v115, v44, v170
	v_cvt_pk_bf16_f32 v116, v46, v174
	v_cvt_pk_bf16_f32 v117, v48, v178
	s_cbranch_vccnz .LBB13_759
	s_mov_b64 s[96:97], 0
	ds_read_b64_tr_b16 v[216:217], v191 offset:49152
	ds_read_b64_tr_b16 v[218:219], v191 offset:49664
	ds_read_b64_tr_b16 v[220:221], v191 offset:50176
	ds_read_b64_tr_b16 v[222:223], v191 offset:50688
	ds_read_b64_tr_b16 v[224:225], v191 offset:51200
	ds_read_b64_tr_b16 v[226:227], v191 offset:51712
	ds_read_b64_tr_b16 v[228:229], v191 offset:52224
	ds_read_b64_tr_b16 v[230:231], v191 offset:52736
	ds_read_b64_tr_b16 v[232:233], v191 offset:53248
	ds_read_b64_tr_b16 v[234:235], v191 offset:53760
	ds_read_b64_tr_b16 v[240:241], v191 offset:54272
	ds_read_b64_tr_b16 v[242:243], v191 offset:54784
	ds_read_b64_tr_b16 v[244:245], v191 offset:55296
	ds_read_b64_tr_b16 v[246:247], v191 offset:55808
	ds_read_b64_tr_b16 v[248:249], v191 offset:56320
	s_waitcnt lgkmcnt(13)
	v_mfma_f32_32x32x16_bf16 v[50:65], v[110:113], v[216:219], 0
	ds_read_b64_tr_b16 v[250:251], v191 offset:56832
	s_waitcnt lgkmcnt(12)
	v_mfma_f32_32x32x16_bf16 v[50:65], v[106:109], v[220:223], v[50:65]
	s_waitcnt lgkmcnt(10)
	v_mfma_f32_32x32x16_bf16 v[50:65], v[118:121], v[224:227], v[50:65]
	s_waitcnt lgkmcnt(8)
	v_mfma_f32_32x32x16_bf16 v[50:65], v[114:117], v[228:231], v[50:65]
	s_waitcnt lgkmcnt(6)
	v_mfma_f32_32x32x16_bf16 v[2:17], v[110:113], v[232:235], 0
	s_waitcnt lgkmcnt(4)
	v_mfma_f32_32x32x16_bf16 v[2:17], v[106:109], v[240:243], v[2:17]
	s_waitcnt lgkmcnt(2)
	v_mfma_f32_32x32x16_bf16 v[2:17], v[118:121], v[244:247], v[2:17]
	s_waitcnt lgkmcnt(0)
	v_mfma_f32_32x32x16_bf16 v[2:17], v[114:117], v[248:251], v[2:17]
	s_branch .LBB13_760

; #define AT_LAS __attribute__((address_space(3)))
; __device__ __forceinline__ s16x4 vtr(AT_LAS const char* p) { return __builtin_bit_cast(s16x4, __builtin_amdgcn_ds_read_tr16_b64_v4i16((AT_LAS v4i16_t*)p)); }
; __device__ __forceinline__ void pv(f32x16 (&o)[2], AT_LAS const char* vp, const u32x4& pw0, const u32x4& pw1, const u32x4& pw2, const u32x4& pw3) {
; #pragma unroll
;     for (int d0 = 0; d0 < 2; ++d0) { s16x4 lo[4], hh[4];
; #pragma unroll
;         for (int ks = 0; ks < 4; ++ks) { lo[ks] = vtr(vp + d0 * 4096 + ks * 1024); hh[ks] = vtr(vp + d0 * 4096 + ks * 1024 + 512); }
;     ...
;         o[d0] = __builtin_amdgcn_mfma_f32_32x32x16_bf16(__builtin_bit_cast(bf16x8, pw0), AT_VF(0), o[d0], 0, 0, 0);
;         o[d0] = __builtin_amdgcn_mfma_f32_32x32x16_bf16(__builtin_bit_cast(bf16x8, pw1), AT_VF(1), o[d0], 0, 0, 0);
;         o[d0] = __builtin_amdgcn_mfma_f32_32x32x16_bf16(__builtin_bit_cast(bf16x8, pw2), AT_VF(2), o[d0], 0, 0, 0);
;         o[d0] = __builtin_amdgcn_mfma_f32_32x32x16_bf16(__builtin_bit_cast(bf16x8, pw3), AT_VF(3), o[d0], 0, 0, 0);
;     ...
;     }
; }
; template <int THRL>
; __device__ __forceinline__ void attn_item(int b, int h, int s, const bf16_t* Q, const bf16_t* KN, const bf16_t* KR, const bf16_t* V, const float* goa  , bf16_t* Y, float* ssqy, AT_LAS char* shm, int wid0) {
;     ...
;         if (late && have) pv(o, vp0 + ((NT - 1) & 3) * VSLOTB, pw0, pw1, pw2, pw3);
.LBB13_785:
	s_and_b64 s[76:77], s[0:1], s[96:97]
	s_and_b64 vcc, exec, s[76:77]
	s_cbranch_vccz .LBB13_787
	s_nop 0
	ds_read_b64_tr_b16 v[216:217], v192 offset:24576
	ds_read_b64_tr_b16 v[218:219], v192 offset:25088
	ds_read_b64_tr_b16 v[220:221], v192 offset:25600
	ds_read_b64_tr_b16 v[222:223], v192 offset:26112
	ds_read_b64_tr_b16 v[224:225], v192 offset:26624
	ds_read_b64_tr_b16 v[226:227], v192 offset:27136
	ds_read_b64_tr_b16 v[228:229], v192 offset:27648
	ds_read_b64_tr_b16 v[230:231], v192 offset:28160
	ds_read_b64_tr_b16 v[232:233], v192 offset:28672
	ds_read_b64_tr_b16 v[234:235], v192 offset:29184
	ds_read_b64_tr_b16 v[240:241], v192 offset:29696
	ds_read_b64_tr_b16 v[242:243], v192 offset:30208
	ds_read_b64_tr_b16 v[244:245], v192 offset:30720
	ds_read_b64_tr_b16 v[246:247], v192 offset:31232
	ds_read_b64_tr_b16 v[248:249], v192 offset:31744
	s_waitcnt lgkmcnt(13)
	v_mfma_f32_32x32x16_bf16 v[50:65], v[110:113], v[216:219], v[50:65]
	ds_read_b64_tr_b16 v[250:251], v192 offset:32256
	s_waitcnt lgkmcnt(12)
	v_mfma_f32_32x32x16_bf16 v[50:65], v[106:109], v[220:223], v[50:65]
	s_waitcnt lgkmcnt(10)
	v_mfma_f32_32x32x16_bf16 v[50:65], v[118:121], v[224:227], v[50:65]
	s_waitcnt lgkmcnt(8)
	v_mfma_f32_32x32x16_bf16 v[50:65], v[114:117], v[228:231], v[50:65]
	s_waitcnt lgkmcnt(6)
	v_mfma_f32_32x32x16_bf16 v[2:17], v[110:113], v[232:235], v[2:17]
	s_waitcnt lgkmcnt(4)
	v_mfma_f32_32x32x16_bf16 v[2:17], v[106:109], v[240:243], v[2:17]
	s_waitcnt lgkmcnt(2)
	v_mfma_f32_32x32x16_bf16 v[2:17], v[118:121], v[244:247], v[2:17]
	s_waitcnt lgkmcnt(0)
	v_mfma_f32_32x32x16_bf16 v[2:17], v[114:117], v[248:251], v[2:17]

; #define AT_LAS __attribute__((address_space(3)))
; __device__ __forceinline__ s16x4 vtr(AT_LAS const char* p) { return __builtin_bit_cast(s16x4, __builtin_amdgcn_ds_read_tr16_b64_v4i16((AT_LAS v4i16_t*)p)); }
; __device__ __forceinline__ void pv(f32x16 (&o)[2], AT_LAS const char* vp, const u32x4& pw0, const u32x4& pw1, const u32x4& pw2, const u32x4& pw3) {
; #pragma unroll
;     for (int d0 = 0; d0 < 2; ++d0) { s16x4 lo[4], hh[4];
; #pragma unroll
;         for (int ks = 0; ks < 4; ++ks) { lo[ks] = vtr(vp + d0 * 4096 + ks * 1024); hh[ks] = vtr(vp + d0 * 4096 + ks * 1024 + 512); }
;     ...
;         o[d0] = __builtin_amdgcn_mfma_f32_32x32x16_bf16(__builtin_bit_cast(bf16x8, pw0), AT_VF(0), o[d0], 0, 0, 0);
;         o[d0] = __builtin_amdgcn_mfma_f32_32x32x16_bf16(__builtin_bit_cast(bf16x8, pw1), AT_VF(1), o[d0], 0, 0, 0);
;         o[d0] = __builtin_amdgcn_mfma_f32_32x32x16_bf16(__builtin_bit_cast(bf16x8, pw2), AT_VF(2), o[d0], 0, 0, 0);
;         o[d0] = __builtin_amdgcn_mfma_f32_32x32x16_bf16(__builtin_bit_cast(bf16x8, pw3), AT_VF(3), o[d0], 0, 0, 0);
;     ...
;     }
; }
; template <int THRL>
; __device__ __forceinline__ void attn_item(int b, int h, int s, const bf16_t* Q, const bf16_t* KN, const bf16_t* KR, const bf16_t* V, const float* goa  , bf16_t* Y, float* ssqy, AT_LAS char* shm, int wid0) {
;     ...
;         if (late && have) pv(o, vp0 + ((NT - 1) & 3) * VSLOTB, pw0, pw1, pw2, pw3);
.LBB13_1763:
	s_and_b64 s[76:77], s[90:91], s[96:97]
	s_and_b64 vcc, exec, s[76:77]
	s_cbranch_vccz .LBB13_1765
	s_nop 0
	ds_read_b64_tr_b16 v[216:217], v192 offset:24576
	ds_read_b64_tr_b16 v[218:219], v192 offset:25088
	ds_read_b64_tr_b16 v[220:221], v192 offset:25600
	ds_read_b64_tr_b16 v[222:223], v192 offset:26112
	ds_read_b64_tr_b16 v[224:225], v192 offset:26624
	ds_read_b64_tr_b16 v[226:227], v192 offset:27136
	ds_read_b64_tr_b16 v[228:229], v192 offset:27648
	ds_read_b64_tr_b16 v[230:231], v192 offset:28160
	ds_read_b64_tr_b16 v[232:233], v192 offset:28672
	ds_read_b64_tr_b16 v[234:235], v192 offset:29184
	ds_read_b64_tr_b16 v[240:241], v192 offset:29696
	ds_read_b64_tr_b16 v[242:243], v192 offset:30208
	ds_read_b64_tr_b16 v[244:245], v192 offset:30720
	ds_read_b64_tr_b16 v[246:247], v192 offset:31232
	ds_read_b64_tr_b16 v[248:249], v192 offset:31744
	s_waitcnt lgkmcnt(13)
	v_mfma_f32_32x32x16_bf16 v[50:65], v[110:113], v[216:219], v[50:65]
	ds_read_b64_tr_b16 v[250:251], v192 offset:32256
	s_waitcnt lgkmcnt(12)
	v_mfma_f32_32x32x16_bf16 v[50:65], v[106:109], v[220:223], v[50:65]
	s_waitcnt lgkmcnt(10)
	v_mfma_f32_32x32x16_bf16 v[50:65], v[118:121], v[224:227], v[50:65]
	s_waitcnt lgkmcnt(8)
	v_mfma_f32_32x32x16_bf16 v[50:65], v[114:117], v[228:231], v[50:65]
	s_waitcnt lgkmcnt(6)
	v_mfma_f32_32x32x16_bf16 v[2:17], v[110:113], v[232:235], v[2:17]
	s_waitcnt lgkmcnt(4)
	v_mfma_f32_32x32x16_bf16 v[2:17], v[106:109], v[240:243], v[2:17]
	s_waitcnt lgkmcnt(2)
	v_mfma_f32_32x32x16_bf16 v[2:17], v[118:121], v[244:247], v[2:17]
	s_waitcnt lgkmcnt(0)
	v_mfma_f32_32x32x16_bf16 v[2:17], v[114:117], v[248:251], v[2:17]
